# static s_setprio 1 for waves 0-3 instead of 4-7
# speedup vs baseline: 1.0064x; 1.0064x over previous
; __global__ void __launch_bounds__(512, 2) mega(Params p) {
;     ...
;     const int wv = __builtin_amdgcn_readfirstlane((int)threadIdx.x >> 6);
_Z4mega6Params:
	s_load_dwordx2 s[60:61], s[0:1], 0x90
	v_and_b32_e32 v1, 0x3ff, v0
	s_mov_b32 s85, s2
	v_readfirstlane_b32 s33, v1
	s_nop 3
	s_cmp_lt_u32 s33, 0x100
	s_cbranch_scc0 .Lprio_skip
	s_setprio 1
